# cache-policy hint on the gla_prep gate-GEMM activation fragments (read once per phase): non-temporal loads
# speedup vs baseline: 1.0099x; 1.0005x over previous
; #define LAS __attribute__((address_space(3)))
; DI void phase_gla_prep(const Params& p, LAS unsigned char* lds) {
;     ...
;     float wg0[16], wg1[16];
; #pragma unroll
;     for (int r = 0; r < 16; ++r) { wg0[r] = p.in[9][r * 1024 + ch0]; wg1[r] = p.in[9][r * 1024 + ch0 + 1]; }
;     const float bs0 = p.in[10][ch0], bs1 = p.in[10][ch0 + 1];
;     for (int u = blockIdx.x; u < 256; u += gridDim.x) {
;         const size_t tokb = (size_t)u * 64;
;         __syncthreads();
;         {
;             LAS bf16_t* wl = (LAS bf16_t*)(lds + 8192);
;             LAS float* part = (LAS float*)(lds + 4096);
;             const bf16_t* wsrc = (const bf16_t*)(p.ws + W_B_IN) + (size_t)6144 * 2048;
; #pragma unroll
;             for (int i = 0; i < 8; ++i) { const int c = tid + i * 512; *(LAS u32x4*)(wl + (c >> 8) * 2056 + (c & 255) * 8) = *(const u32x4*)(wsrc + (size_t)c * 8); }
;             __syncthreads();
;             const int w = tid >> 6, lane = tid & 63, i16 = lane & 15, quad = lane >> 4, mt = w & 3, kh = w >> 2;
;             const bf16_t* xr = (const bf16_t*)(p.ws + XG) + (tokb + 16 * mt + i16) * DM + kh * 1024 + 8 * quad;
;             f32x4 acc = {0.f, 0.f, 0.f, 0.f};
; #pragma unroll 8
;             for (int ks = 0; ks < 32; ++ks) {
;                 const bf16x8 a = *(const bf16x8*)(xr + 32 * ks);
;                 const bf16x8 bb = *(LAS const bf16x8*)(wl + i16 * 2056 + kh * 1024 + 32 * ks + 8 * quad);
.LBB0_506:
	s_or_b64 exec, exec, s[6:7]
	s_cmpk_lt_i32 s2, 0x100
	s_waitcnt lgkmcnt(0)
	v_mov_b32_e32 v0, v181
	s_cselect_b64 s[16:17], -1, 0
	s_cmpk_gt_i32 s2, 0xff
	s_movk_i32 s14, 0x100
	s_barrier
	s_cbranch_scc1 .LBB0_517
	s_cmp_eq_u32 s18, 0x100
	s_cbranch_scc0 .Lgp_orig
	s_load_dwordx2 s[6:7], s[0:1], 0xf0
	s_load_dwordx4 s[8:11], s[0:1], 0x48
	v_and_b32_e32 v96, 63, v181
	v_and_b32_e32 v97, 15, v181
	v_lshrrev_b32_e32 v98, 4, v96
	v_lshrrev_b32_e32 v99, 6, v181
	v_and_b32_e32 v100, 3, v99
	v_lshrrev_b32_e32 v101, 2, v99
	s_nop 1
	v_readfirstlane_b32 s40, v101
	v_lshl_add_u32 v102, v100, 4, v97
	v_lshlrev_b32_e32 v160, 12, v102
	v_lshl_add_u32 v160, v101, 11, v160
	v_lshl_add_u32 v160, v98, 4, v160
	v_mul_u32_u24_e32 v163, 0x1010, v97
	v_lshl_add_u32 v163, v101, 11, v163
	v_lshl_add_u32 v163, v98, 4, v163
	v_add_u32_e32 v163, 0x2000, v163
	v_lshlrev_b32_e32 v161, 4, v181
	v_lshrrev_b32_e32 v103, 8, v181
	v_and_b32_e32 v104, 0xff, v181
	v_mul_u32_u24_e32 v162, 0x1010, v103
	v_lshl_add_u32 v162, v104, 4, v162
	v_add_u32_e32 v162, 0x2000, v162
	v_lshlrev_b32_e32 v105, 2, v98
	v_lshl_add_u32 v105, v100, 4, v105
	v_lshlrev_b32_e32 v164, 6, v105
	v_lshl_add_u32 v164, v97, 2, v164
	v_lshlrev_b32_e32 v168, 2, v105
	v_lshlrev_b32_e32 v165, 3, v181
	v_lshlrev_b32_e32 v166, 2, v181
	v_mov_b32_e32 v167, 0
	v_mov_b32_e32 v186, 0x3fb8aa3b
	v_mov_b32_e32 v187, 0x3fb8aa3b
	v_mov_b32_e32 v188, 0x3d800000
	v_mov_b32_e32 v189, 0x3d800000
	v_mov_b32_e32 v190, 0x3f800000
	v_mov_b32_e32 v191, 0x3f800000
	s_mov_b32 s34, 0xbfb8aa3b
	s_mov_b32 s35, 0xbf317218
	s_mov_b32 s38, 0x3a000000
	s_waitcnt lgkmcnt(0)
	s_add_u32 s26, s6, 0x4000000
	s_addc_u32 s27, s7, 0
	s_lshl_b32 s41, s2, 18
	s_add_u32 s28, s6, 0x1bf00000
	s_addc_u32 s29, s7, 0
	s_add_u32 s28, s28, s41
	s_addc_u32 s29, s29, 0
	s_lshl_b32 s41, s2, 8
	s_add_u32 s42, s6, 0x1ff10000
	s_addc_u32 s43, s7, 0
	s_add_u32 s42, s42, s41
	s_addc_u32 s43, s43, 0
	s_mul_i32 s41, s2, 0xc8000
	s_mul_hi_u32 s44, s2, 0xc8000
	s_add_u32 s30, s6, 0xbf00800
	s_addc_u32 s31, s7, 0
	s_add_u32 s30, s30, s41
	s_addc_u32 s31, s31, s44
	s_add_u32 s30, s30, 0xc4e00
	s_addc_u32 s31, s31, 0
	s_mov_b64 s[46:47], s[30:31]
	s_lshl_b32 s41, s2, 12
	s_add_u32 s48, s6, 0x18700000
	s_addc_u32 s49, s7, 0
	s_add_u32 s48, s48, s41
	s_addc_u32 s49, s49, 0
	s_mov_b64 s[24:25], s[26:27]
	global_load_dwordx4 v[128:131], v161, s[24:25]
	s_add_u32 s24, s24, 0x2000
	s_addc_u32 s25, s25, 0
	global_load_dwordx4 v[132:135], v161, s[24:25]
	s_add_u32 s24, s24, 0x2000
	s_addc_u32 s25, s25, 0
	global_load_dwordx4 v[136:139], v161, s[24:25]
	s_add_u32 s24, s24, 0x2000
	s_addc_u32 s25, s25, 0
	global_load_dwordx4 v[140:143], v161, s[24:25]
	s_add_u32 s24, s24, 0x2000
	s_addc_u32 s25, s25, 0
	global_load_dwordx4 v[144:147], v161, s[24:25]
	s_add_u32 s24, s24, 0x2000
	s_addc_u32 s25, s25, 0
	global_load_dwordx4 v[148:151], v161, s[24:25]
	s_add_u32 s24, s24, 0x2000
	s_addc_u32 s25, s25, 0
	global_load_dwordx4 v[152:155], v161, s[24:25]
	s_add_u32 s24, s24, 0x2000
	s_addc_u32 s25, s25, 0
	global_load_dwordx4 v[156:159], v161, s[24:25]
	global_load_dwordx4 v[0:3], v160, s[28:29] offset:0 nt
	global_load_dwordx4 v[4:7], v160, s[28:29] offset:64 nt
	global_load_dwordx4 v[8:11], v160, s[28:29] offset:128 nt
	global_load_dwordx4 v[12:15], v160, s[28:29] offset:192 nt
	global_load_dwordx4 v[16:19], v160, s[28:29] offset:256 nt
	global_load_dwordx4 v[20:23], v160, s[28:29] offset:320 nt
	global_load_dwordx4 v[24:27], v160, s[28:29] offset:384 nt
	global_load_dwordx4 v[28:31], v160, s[28:29] offset:448 nt
	global_load_dwordx4 v[32:35], v160, s[28:29] offset:512 nt
	global_load_dwordx4 v[36:39], v160, s[28:29] offset:576 nt
	global_load_dwordx4 v[40:43], v160, s[28:29] offset:640 nt
	global_load_dwordx4 v[44:47], v160, s[28:29] offset:704 nt
	global_load_dwordx4 v[48:51], v160, s[28:29] offset:768 nt
	global_load_dwordx4 v[52:55], v160, s[28:29] offset:832 nt
	global_load_dwordx4 v[56:59], v160, s[28:29] offset:896 nt
	global_load_dwordx4 v[60:63], v160, s[28:29] offset:960 nt
	global_load_dwordx4 v[64:67], v160, s[28:29] offset:1024 nt
	global_load_dwordx4 v[68:71], v160, s[28:29] offset:1088 nt
	global_load_dwordx4 v[72:75], v160, s[28:29] offset:1152 nt
	global_load_dwordx4 v[76:79], v160, s[28:29] offset:1216 nt
	global_load_dwordx4 v[80:83], v160, s[28:29] offset:1280 nt
	global_load_dwordx4 v[84:87], v160, s[28:29] offset:1344 nt
	global_load_dwordx4 v[88:91], v160, s[28:29] offset:1408 nt
	global_load_dwordx4 v[92:95], v160, s[28:29] offset:1472 nt
	global_load_dwordx4 v[96:99], v160, s[28:29] offset:1536 nt
	global_load_dwordx4 v[100:103], v160, s[28:29] offset:1600 nt
	global_load_dwordx4 v[104:107], v160, s[28:29] offset:1664 nt
	global_load_dwordx4 v[108:111], v160, s[28:29] offset:1728 nt
	global_load_dwordx4 v[112:115], v160, s[28:29] offset:1792 nt
	global_load_dwordx4 v[116:119], v160, s[28:29] offset:1856 nt
	global_load_dwordx4 v[120:123], v160, s[28:29] offset:1920 nt
	global_load_dwordx4 v[124:127], v160, s[28:29] offset:1984 nt
	global_load_dwordx4 v[182:185], v168, s[42:43]
	s_mov_b64 s[24:25], s[8:9]
	global_load_dwordx2 v[232:233], v165, s[24:25]
	s_add_u32 s24, s24, 0x1000
	s_addc_u32 s25, s25, 0
	global_load_dwordx2 v[234:235], v165, s[24:25]
	s_add_u32 s24, s24, 0x1000
	s_addc_u32 s25, s25, 0
	global_load_dwordx2 v[236:237], v165, s[24:25]
	s_add_u32 s24, s24, 0x1000
	s_addc_u32 s25, s25, 0
	global_load_dwordx2 v[238:239], v165, s[24:25]
	s_add_u32 s24, s24, 0x1000
	s_addc_u32 s25, s25, 0
	global_load_dwordx2 v[240:241], v165, s[24:25]
	s_add_u32 s24, s24, 0x1000
	s_addc_u32 s25, s25, 0
	global_load_dwordx2 v[242:243], v165, s[24:25]
	s_add_u32 s24, s24, 0x1000
	s_addc_u32 s25, s25, 0
	global_load_dwordx2 v[244:245], v165, s[24:25]
	s_add_u32 s24, s24, 0x1000
	s_addc_u32 s25, s25, 0
	global_load_dwordx2 v[246:247], v165, s[24:25]
	s_add_u32 s24, s24, 0x1000
	s_addc_u32 s25, s25, 0
	global_load_dwordx2 v[248:249], v165, s[24:25]
	s_add_u32 s24, s24, 0x1000
	s_addc_u32 s25, s25, 0
	global_load_dwordx2 v[250:251], v165, s[24:25]
	s_add_u32 s24, s24, 0x1000
	s_addc_u32 s25, s25, 0
	global_load_dwordx2 v[252:253], v165, s[24:25]
	s_add_u32 s24, s24, 0x1000
	s_addc_u32 s25, s25, 0
	global_load_dwordx2 v[254:255], v165, s[24:25]
	s_add_u32 s24, s24, 0x1000
	s_addc_u32 s25, s25, 0
	global_load_dwordx2 v[220:221], v165, s[24:25]
	s_add_u32 s24, s24, 0x1000
	s_addc_u32 s25, s25, 0
	global_load_dwordx2 v[222:223], v165, s[24:25]
	s_add_u32 s24, s24, 0x1000
	s_addc_u32 s25, s25, 0
	global_load_dwordx2 v[224:225], v165, s[24:25]
	s_add_u32 s24, s24, 0x1000
	s_addc_u32 s25, s25, 0
	global_load_dwordx2 v[226:227], v165, s[24:25]
	global_load_dwordx2 v[198:199], v165, s[10:11]
	s_waitcnt vmcnt(50)
; #define LAS __attribute__((address_space(3)))
; DI void phase_gla_prep(const Params& p, LAS unsigned char* lds) {
;     ...
;             for (int i = 0; i < 8; ++i) { const int c = tid + i * 512; *(LAS u32x4*)(wl + (c >> 8) * 2056 + (c & 255) * 8) = *(const u32x4*)(wsrc + (size_t)c * 8); }
;             __syncthreads();
;             const int w = tid >> 6, lane = tid & 63, i16 = lane & 15, quad = lane >> 4, mt = w & 3, kh = w >> 2;
;             const bf16_t* xr = (const bf16_t*)(p.ws + XG) + (tokb + 16 * mt + i16) * DM + kh * 1024 + 8 * quad;
;             f32x4 acc = {0.f, 0.f, 0.f, 0.f};
; #pragma unroll 8
;             for (int ks = 0; ks < 32; ++ks) {
;                 const bf16x8 a = *(const bf16x8*)(xr + 32 * ks);
;                 const bf16x8 bb = *(LAS const bf16x8*)(wl + i16 * 2056 + kh * 1024 + 32 * ks + 8 * quad);
;                 acc = __builtin_amdgcn_mfma_f32_16x16x32_bf16(a, bb, acc, 0, 0, 0);
	ds_write_b128 v162, v[128:131] offset:0
	ds_write_b128 v162, v[132:135] offset:8224
	ds_write_b128 v162, v[136:139] offset:16448
	ds_write_b128 v162, v[140:143] offset:24672
	ds_write_b128 v162, v[144:147] offset:32896
	ds_write_b128 v162, v[148:151] offset:41120
	ds_write_b128 v162, v[152:155] offset:49344
	ds_write_b128 v162, v[156:159] offset:57568
	v_mov_b32_e32 v216, 0
	v_mov_b32_e32 v217, 0
	v_mov_b32_e32 v218, 0
	v_mov_b32_e32 v219, 0
	s_waitcnt lgkmcnt(0)
	s_barrier
	ds_read_b128 v[200:203], v163 offset:0
	ds_read_b128 v[204:207], v163 offset:64
	ds_read_b128 v[208:211], v163 offset:128
	ds_read_b128 v[212:215], v163 offset:192
	s_waitcnt vmcnt(49) lgkmcnt(3)
	v_mfma_f32_16x16x32_bf16 v[216:219], v[0:3], v[200:203], v[216:219]
	s_waitcnt vmcnt(48) lgkmcnt(2)
	v_mfma_f32_16x16x32_bf16 v[216:219], v[4:7], v[204:207], v[216:219]
	s_waitcnt vmcnt(47) lgkmcnt(1)
	v_mfma_f32_16x16x32_bf16 v[216:219], v[8:11], v[208:211], v[216:219]
	s_waitcnt vmcnt(46) lgkmcnt(0)
	v_mfma_f32_16x16x32_bf16 v[216:219], v[12:15], v[212:215], v[216:219]
	s_nop 3
	ds_read_b128 v[200:203], v163 offset:256
	ds_read_b128 v[204:207], v163 offset:320
	ds_read_b128 v[208:211], v163 offset:384
	ds_read_b128 v[212:215], v163 offset:448
	s_waitcnt vmcnt(45) lgkmcnt(3)
	v_mfma_f32_16x16x32_bf16 v[216:219], v[16:19], v[200:203], v[216:219]
	s_waitcnt vmcnt(44) lgkmcnt(2)
	v_mfma_f32_16x16x32_bf16 v[216:219], v[20:23], v[204:207], v[216:219]
	s_waitcnt vmcnt(43) lgkmcnt(1)
	v_mfma_f32_16x16x32_bf16 v[216:219], v[24:27], v[208:211], v[216:219]
	s_waitcnt vmcnt(42) lgkmcnt(0)
	v_mfma_f32_16x16x32_bf16 v[216:219], v[28:31], v[212:215], v[216:219]
	s_nop 3
	ds_read_b128 v[200:203], v163 offset:512
	ds_read_b128 v[204:207], v163 offset:576
	ds_read_b128 v[208:211], v163 offset:640
	ds_read_b128 v[212:215], v163 offset:704
	s_waitcnt vmcnt(41) lgkmcnt(3)
	v_mfma_f32_16x16x32_bf16 v[216:219], v[32:35], v[200:203], v[216:219]
	s_waitcnt vmcnt(40) lgkmcnt(2)
	v_mfma_f32_16x16x32_bf16 v[216:219], v[36:39], v[204:207], v[216:219]
	s_waitcnt vmcnt(39) lgkmcnt(1)
	v_mfma_f32_16x16x32_bf16 v[216:219], v[40:43], v[208:211], v[216:219]
	s_waitcnt vmcnt(38) lgkmcnt(0)
	v_mfma_f32_16x16x32_bf16 v[216:219], v[44:47], v[212:215], v[216:219]
	s_nop 3
	ds_read_b128 v[200:203], v163 offset:768
	ds_read_b128 v[204:207], v163 offset:832
	ds_read_b128 v[208:211], v163 offset:896
	ds_read_b128 v[212:215], v163 offset:960
	s_waitcnt vmcnt(37) lgkmcnt(3)
	v_mfma_f32_16x16x32_bf16 v[216:219], v[48:51], v[200:203], v[216:219]
	s_waitcnt vmcnt(36) lgkmcnt(2)
	v_mfma_f32_16x16x32_bf16 v[216:219], v[52:55], v[204:207], v[216:219]
	s_waitcnt vmcnt(35) lgkmcnt(1)
	v_mfma_f32_16x16x32_bf16 v[216:219], v[56:59], v[208:211], v[216:219]
	s_waitcnt vmcnt(34) lgkmcnt(0)
	v_mfma_f32_16x16x32_bf16 v[216:219], v[60:63], v[212:215], v[216:219]
	s_nop 3
	ds_read_b128 v[200:203], v163 offset:1024
	ds_read_b128 v[204:207], v163 offset:1088
	ds_read_b128 v[208:211], v163 offset:1152
	ds_read_b128 v[212:215], v163 offset:1216
	s_waitcnt vmcnt(33) lgkmcnt(3)
	v_mfma_f32_16x16x32_bf16 v[216:219], v[64:67], v[200:203], v[216:219]
	s_waitcnt vmcnt(32) lgkmcnt(2)
	v_mfma_f32_16x16x32_bf16 v[216:219], v[68:71], v[204:207], v[216:219]
	s_waitcnt vmcnt(31) lgkmcnt(1)
	v_mfma_f32_16x16x32_bf16 v[216:219], v[72:75], v[208:211], v[216:219]
	s_waitcnt vmcnt(30) lgkmcnt(0)
	v_mfma_f32_16x16x32_bf16 v[216:219], v[76:79], v[212:215], v[216:219]
	s_nop 3
	ds_read_b128 v[200:203], v163 offset:1280
	ds_read_b128 v[204:207], v163 offset:1344
	ds_read_b128 v[208:211], v163 offset:1408
	ds_read_b128 v[212:215], v163 offset:1472
	s_waitcnt vmcnt(29) lgkmcnt(3)
	v_mfma_f32_16x16x32_bf16 v[216:219], v[80:83], v[200:203], v[216:219]
	s_waitcnt vmcnt(28) lgkmcnt(2)
	v_mfma_f32_16x16x32_bf16 v[216:219], v[84:87], v[204:207], v[216:219]
	s_waitcnt vmcnt(27) lgkmcnt(1)
	v_mfma_f32_16x16x32_bf16 v[216:219], v[88:91], v[208:211], v[216:219]
	s_waitcnt vmcnt(26) lgkmcnt(0)
	v_mfma_f32_16x16x32_bf16 v[216:219], v[92:95], v[212:215], v[216:219]
	s_nop 3
	ds_read_b128 v[200:203], v163 offset:1536
	ds_read_b128 v[204:207], v163 offset:1600
	ds_read_b128 v[208:211], v163 offset:1664
	ds_read_b128 v[212:215], v163 offset:1728
	s_waitcnt vmcnt(25) lgkmcnt(3)
; #define LAS __attribute__((address_space(3)))
; DI void phase_gla_prep(const Params& p, LAS unsigned char* lds) {
;     ...
;             for (int ks = 0; ks < 32; ++ks) {
;                 const bf16x8 a = *(const bf16x8*)(xr + 32 * ks);
;                 const bf16x8 bb = *(LAS const bf16x8*)(wl + i16 * 2056 + kh * 1024 + 32 * ks + 8 * quad);
;                 acc = __builtin_amdgcn_mfma_f32_16x16x32_bf16(a, bb, acc, 0, 0, 0);
;             }
;             if (kh == 1) {
; #pragma unroll
;                 for (int j = 0; j < 4; ++j) part[(16 * mt + 4 * quad + j) * 16 + i16] = acc[j]; }
;     ...
;             unsigned kw[16];
; #pragma unroll
;             for (int i = 0; i < 16; ++i) kw[i] = *(const unsigned*)(big + (tokb + tg * 16 + i) * 6400 + 1024 + ch0);
	v_mfma_f32_16x16x32_bf16 v[216:219], v[96:99], v[200:203], v[216:219]
	s_waitcnt vmcnt(24) lgkmcnt(2)
	v_mfma_f32_16x16x32_bf16 v[216:219], v[100:103], v[204:207], v[216:219]
	s_waitcnt vmcnt(23) lgkmcnt(1)
	v_mfma_f32_16x16x32_bf16 v[216:219], v[104:107], v[208:211], v[216:219]
	s_waitcnt vmcnt(22) lgkmcnt(0)
	v_mfma_f32_16x16x32_bf16 v[216:219], v[108:111], v[212:215], v[216:219]
	s_nop 3
	ds_read_b128 v[200:203], v163 offset:1792
	ds_read_b128 v[204:207], v163 offset:1856
	ds_read_b128 v[208:211], v163 offset:1920
	ds_read_b128 v[212:215], v163 offset:1984
	s_waitcnt vmcnt(21) lgkmcnt(3)
	v_mfma_f32_16x16x32_bf16 v[216:219], v[112:115], v[200:203], v[216:219]
	s_waitcnt vmcnt(20) lgkmcnt(2)
	v_mfma_f32_16x16x32_bf16 v[216:219], v[116:119], v[204:207], v[216:219]
	s_waitcnt vmcnt(19) lgkmcnt(1)
	v_mfma_f32_16x16x32_bf16 v[216:219], v[120:123], v[208:211], v[216:219]
	s_waitcnt vmcnt(18) lgkmcnt(0)
	v_mfma_f32_16x16x32_bf16 v[216:219], v[124:127], v[212:215], v[216:219]
	s_nop 3
	s_waitcnt vmcnt(0)
	global_load_dword v0, v166, s[30:31]
	s_sub_u32 s30, s30, 0x3200
	s_subb_u32 s31, s31, 0
	global_load_dword v1, v166, s[30:31]
	s_sub_u32 s30, s30, 0x3200
	s_subb_u32 s31, s31, 0
	global_load_dword v2, v166, s[30:31]
	s_sub_u32 s30, s30, 0x3200
	s_subb_u32 s31, s31, 0
	global_load_dword v3, v166, s[30:31]
	s_sub_u32 s30, s30, 0x3200
	s_subb_u32 s31, s31, 0
	global_load_dword v4, v166, s[30:31]
	s_sub_u32 s30, s30, 0x3200
	s_subb_u32 s31, s31, 0
	global_load_dword v5, v166, s[30:31]
	s_sub_u32 s30, s30, 0x3200
	s_subb_u32 s31, s31, 0
	global_load_dword v6, v166, s[30:31]
	s_sub_u32 s30, s30, 0x3200
	s_subb_u32 s31, s31, 0
	global_load_dword v7, v166, s[30:31]
	s_sub_u32 s30, s30, 0x3200
	s_subb_u32 s31, s31, 0
	global_load_dword v8, v166, s[30:31]
	s_sub_u32 s30, s30, 0x3200
	s_subb_u32 s31, s31, 0
	global_load_dword v9, v166, s[30:31]
	s_sub_u32 s30, s30, 0x3200
	s_subb_u32 s31, s31, 0
	global_load_dword v10, v166, s[30:31]
	s_sub_u32 s30, s30, 0x3200
	s_subb_u32 s31, s31, 0
	global_load_dword v11, v166, s[30:31]
	s_sub_u32 s30, s30, 0x3200
	s_subb_u32 s31, s31, 0
	global_load_dword v12, v166, s[30:31]
	s_sub_u32 s30, s30, 0x3200
	s_subb_u32 s31, s31, 0
	global_load_dword v13, v166, s[30:31]
	s_sub_u32 s30, s30, 0x3200
	s_subb_u32 s31, s31, 0
	global_load_dword v14, v166, s[30:31]
	s_sub_u32 s30, s30, 0x3200
	s_subb_u32 s31, s31, 0
	global_load_dword v15, v166, s[30:31]
	s_sub_u32 s30, s30, 0x3200
	s_subb_u32 s31, s31, 0
	global_load_dword v16, v166, s[30:31]
	s_sub_u32 s30, s30, 0x3200
	s_subb_u32 s31, s31, 0
	global_load_dword v17, v166, s[30:31]
	s_sub_u32 s30, s30, 0x3200
	s_subb_u32 s31, s31, 0
	global_load_dword v18, v166, s[30:31]
	s_sub_u32 s30, s30, 0x3200
	s_subb_u32 s31, s31, 0
	global_load_dword v19, v166, s[30:31]
	s_sub_u32 s30, s30, 0x3200
	s_subb_u32 s31, s31, 0
	global_load_dword v20, v166, s[30:31]
	s_sub_u32 s30, s30, 0x3200
	s_subb_u32 s31, s31, 0
	global_load_dword v21, v166, s[30:31]
	s_sub_u32 s30, s30, 0x3200
	s_subb_u32 s31, s31, 0
	global_load_dword v22, v166, s[30:31]
	s_sub_u32 s30, s30, 0x3200
	s_subb_u32 s31, s31, 0
	global_load_dword v23, v166, s[30:31]
	s_sub_u32 s30, s30, 0x3200
	s_subb_u32 s31, s31, 0
	global_load_dword v24, v166, s[30:31]
	s_sub_u32 s30, s30, 0x3200
	s_subb_u32 s31, s31, 0
	global_load_dword v25, v166, s[30:31]
	s_sub_u32 s30, s30, 0x3200
	s_subb_u32 s31, s31, 0
	global_load_dword v26, v166, s[30:31]
	s_sub_u32 s30, s30, 0x3200
	s_subb_u32 s31, s31, 0
	global_load_dword v27, v166, s[30:31]
	s_sub_u32 s30, s30, 0x3200
	s_subb_u32 s31, s31, 0
	global_load_dword v28, v166, s[30:31]
	s_sub_u32 s30, s30, 0x3200
	s_subb_u32 s31, s31, 0
	global_load_dword v29, v166, s[30:31]
	s_sub_u32 s30, s30, 0x3200
	s_subb_u32 s31, s31, 0
	global_load_dword v30, v166, s[30:31]
	s_sub_u32 s30, s30, 0x3200
	s_subb_u32 s31, s31, 0
	global_load_dword v31, v166, s[30:31]
	s_sub_u32 s30, s30, 0x3200
	s_subb_u32 s31, s31, 0
	s_nop 7
	s_nop 7
	s_cmp_eq_u32 s40, 0
	s_cbranch_scc1 .Lgp_k0a
	ds_write_b32 v164, v216 offset:4096
	ds_write_b32 v164, v217 offset:4160
	ds_write_b32 v164, v218 offset:4224
	ds_write_b32 v164, v219 offset:4288
